# MLA attention main loop: exps of the current tile interleaved into P.V MFMA gaps, packs into row-sum MFMA gaps (reorder + rename only)
# baseline (speedup 1.0000x reference)
.LBB0_635:
	s_or_b64 exec, exec, s[8:9]
	global_load_dwordx4 v[162:165], v[184:185], off
	s_add_i32 s8, s10, -1
	s_and_b32 s11, s8, 1
	s_mul_i32 s8, s11, 0x3400
	v_add_u32_e32 v174, s8, v196
	ds_read_b128 v[80:83], v174
	ds_read_b128 v[204:207], v174 offset:32
	ds_read_b128 v[208:211], v174 offset:6656
	ds_read_b128 v[214:217], v174 offset:6688
	s_xor_b32 s8, s11, 1
	s_mulk_i32 s8, 0x3000
	v_add_u32_e32 v176, s8, v198
	s_waitcnt lgkmcnt(3)
	v_mfma_f32_32x32x16_bf16 v[96:111], v[80:83], v[142:145], v[48:63]
	ds_read_b128 v[222:225], v174 offset:64
	ds_read_b64_tr_b16 v[226:227], v176 offset:26624
	ds_read_b64_tr_b16 v[228:229], v176 offset:28160
	s_waitcnt lgkmcnt(4)
	v_mfma_f32_32x32x16_bf16 v[80:95], v[208:211], v[142:145], v[48:63]
	ds_read_b128 v[208:211], v174 offset:6720
	ds_read_b64_tr_b16 v[230:231], v176 offset:26688
	ds_read_b64_tr_b16 v[232:233], v176 offset:28224
	v_mfma_f32_32x32x16_bf16 v[96:111], v[204:207], v[138:141], v[96:111]
	ds_read_b128 v[204:207], v174 offset:96
	ds_read_b64_tr_b16 v[234:235], v176 offset:29696
	ds_read_b64_tr_b16 v[236:237], v176 offset:31232
	s_waitcnt lgkmcnt(9)
	v_mfma_f32_32x32x16_bf16 v[80:95], v[214:217], v[138:141], v[80:95]
	ds_read_b128 v[214:217], v174 offset:6752
	ds_read_b64_tr_b16 v[238:239], v176 offset:29760
	ds_read_b64_tr_b16 v[240:241], v176 offset:31296
	s_waitcnt lgkmcnt(11)
	v_mfma_f32_32x32x16_bf16 v[96:111], v[222:225], v[134:137], v[96:111]
	ds_read_b128 v[222:225], v174 offset:128
	ds_read_b64_tr_b16 v[242:243], v176 offset:32768
	ds_read_b64_tr_b16 v[244:245], v176 offset:34304
	s_waitcnt lgkmcnt(11)
	v_mfma_f32_32x32x16_bf16 v[80:95], v[208:211], v[134:137], v[80:95]
	ds_read_b128 v[208:211], v174 offset:6784
	ds_read_b64_tr_b16 v[246:247], v176 offset:32832
	ds_read_b64_tr_b16 v[248:249], v176 offset:34368
	s_waitcnt lgkmcnt(11)
	v_mfma_f32_32x32x16_bf16 v[96:111], v[204:207], v[130:133], v[96:111]
	ds_read_b128 v[204:207], v174 offset:160
	ds_read_b64_tr_b16 v[186:187], v176 offset:35840
	ds_read_b64_tr_b16 v[188:189], v176 offset:37376
	s_waitcnt lgkmcnt(11)
	v_mfma_f32_32x32x16_bf16 v[80:95], v[214:217], v[130:133], v[80:95]
	ds_read_b128 v[214:217], v174 offset:6816
	ds_read_b64_tr_b16 v[174:175], v176 offset:35904
	ds_read_b64_tr_b16 v[176:177], v176 offset:37440
	s_waitcnt lgkmcnt(11)
	v_mfma_f32_32x32x16_bf16 v[96:111], v[222:225], v[120:123], v[96:111]
	s_waitcnt lgkmcnt(8)
	v_mfma_f32_32x32x16_bf16 v[80:95], v[208:211], v[120:123], v[80:95]
	s_waitcnt lgkmcnt(5)
	v_mfma_f32_32x32x16_bf16 v[96:111], v[204:207], v[116:119], v[96:111]
	s_waitcnt lgkmcnt(2)
	v_mfma_f32_32x32x16_bf16 v[80:95], v[214:217], v[116:119], v[80:95]
	v_mfma_f32_32x32x16_bf16 v[32:47], v[226:229], v[158:161], v[32:47]
	v_mfma_f32_32x32x16_bf16 v[16:31], v[230:233], v[158:161], v[16:31]
	s_nop 7
	v_mfma_f32_32x32x16_bf16 v[32:47], v[234:237], v[154:157], v[32:47]
	v_exp_f32_e32 v206, v96
	v_exp_f32_e32 v207, v97
	v_exp_f32_e32 v98, v98
	v_exp_f32_e32 v99, v99
	v_mfma_f32_32x32x16_bf16 v[16:31], v[238:241], v[154:157], v[16:31]
	v_exp_f32_e32 v208, v100
	v_exp_f32_e32 v209, v101
	v_exp_f32_e32 v210, v102
	v_exp_f32_e32 v211, v103
	v_mfma_f32_32x32x16_bf16 v[32:47], v[242:245], v[150:153], v[32:47]
	v_exp_f32_e32 v104, v104
	v_exp_f32_e32 v214, v105
	v_exp_f32_e32 v105, v106
	v_exp_f32_e32 v215, v107
	v_mfma_f32_32x32x16_bf16 v[16:31], v[246:249], v[150:153], v[16:31]
	v_exp_f32_e32 v106, v108
	v_exp_f32_e32 v108, v109
	v_exp_f32_e32 v107, v110
	v_exp_f32_e32 v109, v111
	v_mfma_f32_32x32x16_bf16 v[32:47], v[186:189], v[146:149], v[32:47]
	v_exp_f32_e32 v80, v80
	v_exp_f32_e32 v81, v81
	v_exp_f32_e32 v82, v82
	v_exp_f32_e32 v83, v83
	s_waitcnt lgkmcnt(0)
	v_mfma_f32_32x32x16_bf16 v[16:31], v[174:177], v[146:149], v[16:31]
	v_exp_f32_e32 v84, v84
	v_exp_f32_e32 v85, v85
	v_exp_f32_e32 v86, v86
	v_exp_f32_e32 v87, v87
	v_mfma_f32_32x32x16_bf16 v[64:79], v[112:115], v[158:161], v[64:79]
	v_exp_f32_e32 v88, v88
	v_exp_f32_e32 v89, v89
	v_exp_f32_e32 v90, v90
	v_exp_f32_e32 v91, v91
	v_mfma_f32_32x32x16_bf16 v[64:79], v[112:115], v[154:157], v[64:79]
	v_exp_f32_e32 v92, v92
	v_exp_f32_e32 v93, v93
	v_exp_f32_e32 v94, v94
	v_exp_f32_e32 v95, v95
	v_mfma_f32_32x32x16_bf16 v[64:79], v[112:115], v[150:153], v[64:79]
	v_cvt_pk_bf16_f32 v97, v90, v91
	v_cvt_pk_bf16_f32 v96, v88, v89
	v_cvt_pk_bf16_f32 v103, v86, v87
	v_cvt_pk_bf16_f32 v102, v84, v85
	v_cvt_pk_bf16_f32 v101, v82, v83
	v_cvt_pk_bf16_f32 v100, v80, v81
	v_cvt_pk_bf16_f32 v107, v107, v109
	v_cvt_pk_bf16_f32 v106, v106, v108
	v_mfma_f32_32x32x16_bf16 v[64:79], v[112:115], v[146:149], v[64:79]
	v_cvt_pk_bf16_f32 v105, v105, v215
	v_cvt_pk_bf16_f32 v104, v104, v214
	v_cvt_pk_bf16_f32 v111, v210, v211
	v_cvt_pk_bf16_f32 v110, v208, v209
	v_cvt_pk_bf16_f32 v109, v98, v99
	v_cvt_pk_bf16_f32 v108, v206, v207
	v_cvt_pk_bf16_f32 v98, v92, v93
	v_cvt_pk_bf16_f32 v99, v94, v95
	s_bitcmp1_b32 s10, 0
	s_cselect_b32 s8, 0x3400, 0
	s_add_i32 s16, s8, 0
	v_add_u32_e32 v174, s16, v194
	s_waitcnt vmcnt(1)
	ds_write_b128 v174, v[166:169]
	s_and_saveexec_b64 s[8:9], s[0:1]
	v_add_u32_e32 v166, s16, v195
	ds_write_b128 v166, v[124:127]
	s_or_b64 exec, exec, s[8:9]
	s_mulk_i32 s11, 0x3000
	s_add_i32 s10, s10, 1
	s_mov_b64 s[8:9], 0x2000
	v_add_u32_e32 v80, s11, v197
	v_lshl_add_u64 v[184:185], v[184:185], 0, s[8:9]
	v_lshl_add_u64 v[190:191], v[190:191], 0, s[92:93]
	s_cmpk_eq_i32 s10, 0x80
	v_lshl_add_u64 v[192:193], v[192:193], 0, s[92:93]
	s_waitcnt vmcnt(0)
	ds_write_b128 v80, v[162:165] offset:26624
	s_waitcnt lgkmcnt(0)
	s_barrier
	s_cbranch_scc1 .LBB0_639
	v_mov_b32_e32 v158, v108
	v_mov_b32_e32 v159, v109
	v_mov_b32_e32 v160, v110
	v_mov_b32_e32 v161, v111
	v_mov_b32_e32 v154, v104
	v_mov_b32_e32 v155, v105
	v_mov_b32_e32 v156, v106
	v_mov_b32_e32 v157, v107
	v_mov_b32_e32 v150, v100
	v_mov_b32_e32 v151, v101
	v_mov_b32_e32 v152, v102
	v_mov_b32_e32 v153, v103
	v_mov_b32_e32 v146, v96
	v_mov_b32_e32 v147, v97
	v_mov_b32_e32 v148, v98
	v_mov_b32_e32 v149, v99
	global_load_dwordx4 v[166:169], v[190:191], off
	s_and_saveexec_b64 s[8:9], s[0:1]
	s_cbranch_execnz .LBB0_634
	s_branch .LBB0_635
